# stack10 with the cache-conversion loads issued at the start of the P2 tail and the prompt-V f32 cache stores re-paired to 64 contiguous bytes per row per instruction
# baseline (speedup 1.0000x reference)
.LBB0_175:
	s_andn2_b64 vcc, exec, s[8:9]
	s_cbranch_vccnz .LBB0_240
	s_lshl_b32 s8, s20, 8
	s_mul_i32 s12, s50, 0x600
	s_add_i32 s13, s3, 0x200
	s_mul_hi_i32 s9, s50, 0x600
	s_add_u32 s12, s12, s13
	s_addc_u32 s13, s9, 0
	v_add_u32_e32 v130, s2, v154
	s_or_b32 s8, s8, s25
	v_ashrrev_i32_e32 v131, 31, v130
	v_lshl_add_u32 v136, v146, 3, s8
	v_lshlrev_b64 v[138:139], 9, v[130:131]
	v_add_u32_e32 v134, 0xfffff600, v136
	v_cndmask_b32_e64 v137, 0, 1, s[10:11]
	v_ashrrev_i32_e32 v135, 31, v134
	s_mov_b64 s[86:87], -1
	v_cmp_ne_u32_e64 s[8:9], 1, v137
	s_andn2_b64 vcc, exec, s[10:11]
	v_lshl_add_u64 v[140:141], v[138:139], 1, s[64:65]
	v_lshl_add_u64 v[138:139], v[138:139], 2, s[72:73]
	v_cvt_pk_bf16_f32 v130, v126, v127
	v_cvt_pk_bf16_f32 v131, v128, v129
	v_cvt_pk_bf16_f32 v132, v122, v123
	v_cvt_pk_bf16_f32 v133, v124, v125
	s_cbranch_vccnz .LBB0_178
	v_lshl_add_u64 v[142:143], v[134:135], 1, v[140:141]
	global_store_dwordx4 v[142:143], v[130:133], off
	v_lshl_add_u64 v[142:143], v[134:135], 2, v[138:139]
	s_mov_b64 s[86:87], 0
	v_mbcnt_lo_u32_b32 v252, -1, 0
	v_mbcnt_hi_u32_b32 v252, -1, v252
	v_lshrrev_b32_e32 v252, 4, v252
	v_lshlrev_b32_e32 v252, 4, v252
	v_permlane16_swap_b32_e32 v126, v122
	v_permlane16_swap_b32_e32 v127, v123
	v_permlane16_swap_b32_e32 v128, v124
	v_permlane16_swap_b32_e32 v129, v125
	v_sub_u32_e32 v250, v142, v252
	v_mov_b32_e32 v251, v143
	v_permlane32_swap_b32_e32 v126, v122
	v_permlane32_swap_b32_e32 v127, v123
	v_permlane32_swap_b32_e32 v128, v124
	v_permlane32_swap_b32_e32 v129, v125
	s_nop 1
	global_store_dwordx4 v[250:251], v[126:129], off nt
	global_store_dwordx4 v[250:251], v[122:125], off offset:64 nt

.LBB0_180:
	v_add_u32_e32 v136, 0xfffff680, v136
	v_ashrrev_i32_e32 v137, 31, v136
	s_and_b64 vcc, exec, s[8:9]
	s_mov_b64 s[86:87], -1
	v_cvt_pk_bf16_f32 v130, v118, v119
	v_cvt_pk_bf16_f32 v131, v120, v121
	v_cvt_pk_bf16_f32 v132, v114, v115
	v_cvt_pk_bf16_f32 v133, v116, v117
	s_cbranch_vccnz .LBB0_182
	v_lshl_add_u64 v[140:141], v[136:137], 1, v[140:141]
	v_lshl_add_u64 v[138:139], v[136:137], 2, v[138:139]
	s_mov_b64 s[86:87], 0
	global_store_dwordx4 v[140:141], v[130:133], off
	v_mbcnt_lo_u32_b32 v252, -1, 0
	v_mbcnt_hi_u32_b32 v252, -1, v252
	v_lshrrev_b32_e32 v252, 4, v252
	v_lshlrev_b32_e32 v252, 4, v252
	v_permlane16_swap_b32_e32 v118, v114
	v_permlane16_swap_b32_e32 v119, v115
	v_permlane16_swap_b32_e32 v120, v116
	v_permlane16_swap_b32_e32 v121, v117
	v_sub_u32_e32 v250, v138, v252
	v_mov_b32_e32 v251, v139
	v_permlane32_swap_b32_e32 v118, v114
	v_permlane32_swap_b32_e32 v119, v115
	v_permlane32_swap_b32_e32 v120, v116
	v_permlane32_swap_b32_e32 v121, v117
	s_nop 1
	global_store_dwordx4 v[250:251], v[118:121], off nt
	global_store_dwordx4 v[250:251], v[114:117], off offset:64 nt

.LBB0_184:
	v_add_u32_e32 v142, 16, v154
	s_nop 0
	v_add_u32_e32 v130, s2, v142
	v_ashrrev_i32_e32 v131, 31, v130
	v_lshlrev_b64 v[138:139], 9, v[130:131]
	s_mov_b64 s[86:87], -1
	s_and_b64 vcc, exec, s[8:9]
	v_lshl_add_u64 v[140:141], v[138:139], 1, s[64:65]
	v_lshl_add_u64 v[138:139], v[138:139], 2, s[72:73]
	v_cvt_pk_bf16_f32 v130, v110, v111
	v_cvt_pk_bf16_f32 v131, v112, v113
	v_cvt_pk_bf16_f32 v132, v106, v107
	v_cvt_pk_bf16_f32 v133, v108, v109
	s_cbranch_vccnz .LBB0_186
	v_lshl_add_u64 v[144:145], v[134:135], 1, v[140:141]
	global_store_dwordx4 v[144:145], v[130:133], off
	v_lshl_add_u64 v[144:145], v[134:135], 2, v[138:139]
	s_mov_b64 s[86:87], 0
	v_mbcnt_lo_u32_b32 v252, -1, 0
	v_mbcnt_hi_u32_b32 v252, -1, v252
	v_lshrrev_b32_e32 v252, 4, v252
	v_lshlrev_b32_e32 v252, 4, v252
	v_permlane16_swap_b32_e32 v110, v106
	v_permlane16_swap_b32_e32 v111, v107
	v_permlane16_swap_b32_e32 v112, v108
	v_permlane16_swap_b32_e32 v113, v109
	v_sub_u32_e32 v250, v144, v252
	v_mov_b32_e32 v251, v145
	v_permlane32_swap_b32_e32 v110, v106
	v_permlane32_swap_b32_e32 v111, v107
	v_permlane32_swap_b32_e32 v112, v108
	v_permlane32_swap_b32_e32 v113, v109
	s_nop 1
	global_store_dwordx4 v[250:251], v[110:113], off nt
	global_store_dwordx4 v[250:251], v[106:109], off offset:64 nt

.LBB0_188:
	s_and_b64 vcc, exec, s[8:9]
	s_mov_b64 s[86:87], -1
	v_cvt_pk_bf16_f32 v130, v102, v103
	v_cvt_pk_bf16_f32 v131, v104, v105
	v_cvt_pk_bf16_f32 v132, v98, v99
	v_cvt_pk_bf16_f32 v133, v100, v101
	s_cbranch_vccnz .LBB0_190
	v_lshl_add_u64 v[140:141], v[136:137], 1, v[140:141]
	v_lshl_add_u64 v[138:139], v[136:137], 2, v[138:139]
	s_mov_b64 s[86:87], 0
	global_store_dwordx4 v[140:141], v[130:133], off
	v_mbcnt_lo_u32_b32 v252, -1, 0
	v_mbcnt_hi_u32_b32 v252, -1, v252
	v_lshrrev_b32_e32 v252, 4, v252
	v_lshlrev_b32_e32 v252, 4, v252
	v_permlane16_swap_b32_e32 v102, v98
	v_permlane16_swap_b32_e32 v103, v99
	v_permlane16_swap_b32_e32 v104, v100
	v_permlane16_swap_b32_e32 v105, v101
	v_sub_u32_e32 v250, v138, v252
	v_mov_b32_e32 v251, v139
	v_permlane32_swap_b32_e32 v102, v98
	v_permlane32_swap_b32_e32 v103, v99
	v_permlane32_swap_b32_e32 v104, v100
	v_permlane32_swap_b32_e32 v105, v101
	s_nop 1
	global_store_dwordx4 v[250:251], v[102:105], off nt
	global_store_dwordx4 v[250:251], v[98:101], off offset:64 nt

.LBB0_192:
	v_add_u32_e32 v142, 32, v154
	s_nop 0
	v_add_u32_e32 v130, s2, v142
	v_ashrrev_i32_e32 v131, 31, v130
	v_lshlrev_b64 v[138:139], 9, v[130:131]
	s_mov_b64 s[86:87], -1
	s_and_b64 vcc, exec, s[8:9]
	v_lshl_add_u64 v[140:141], v[138:139], 1, s[64:65]
	v_lshl_add_u64 v[138:139], v[138:139], 2, s[72:73]
	v_cvt_pk_bf16_f32 v130, v94, v95
	v_cvt_pk_bf16_f32 v131, v96, v97
	v_cvt_pk_bf16_f32 v132, v90, v91
	v_cvt_pk_bf16_f32 v133, v92, v93
	s_cbranch_vccnz .LBB0_194
	v_lshl_add_u64 v[144:145], v[134:135], 1, v[140:141]
	global_store_dwordx4 v[144:145], v[130:133], off
	v_lshl_add_u64 v[144:145], v[134:135], 2, v[138:139]
	s_mov_b64 s[86:87], 0
	v_mbcnt_lo_u32_b32 v252, -1, 0
	v_mbcnt_hi_u32_b32 v252, -1, v252
	v_lshrrev_b32_e32 v252, 4, v252
	v_lshlrev_b32_e32 v252, 4, v252
	v_permlane16_swap_b32_e32 v94, v90
	v_permlane16_swap_b32_e32 v95, v91
	v_permlane16_swap_b32_e32 v96, v92
	v_permlane16_swap_b32_e32 v97, v93
	v_sub_u32_e32 v250, v144, v252
	v_mov_b32_e32 v251, v145
	v_permlane32_swap_b32_e32 v94, v90
	v_permlane32_swap_b32_e32 v95, v91
	v_permlane32_swap_b32_e32 v96, v92
	v_permlane32_swap_b32_e32 v97, v93
	s_nop 1
	global_store_dwordx4 v[250:251], v[94:97], off nt
	global_store_dwordx4 v[250:251], v[90:93], off offset:64 nt

.LBB0_196:
	s_and_b64 vcc, exec, s[8:9]
	s_mov_b64 s[86:87], -1
	v_cvt_pk_bf16_f32 v130, v86, v87
	v_cvt_pk_bf16_f32 v131, v88, v89
	v_cvt_pk_bf16_f32 v132, v82, v83
	v_cvt_pk_bf16_f32 v133, v84, v85
	s_cbranch_vccnz .LBB0_198
	v_lshl_add_u64 v[140:141], v[136:137], 1, v[140:141]
	v_lshl_add_u64 v[138:139], v[136:137], 2, v[138:139]
	s_mov_b64 s[86:87], 0
	global_store_dwordx4 v[140:141], v[130:133], off
	v_mbcnt_lo_u32_b32 v252, -1, 0
	v_mbcnt_hi_u32_b32 v252, -1, v252
	v_lshrrev_b32_e32 v252, 4, v252
	v_lshlrev_b32_e32 v252, 4, v252
	v_permlane16_swap_b32_e32 v86, v82
	v_permlane16_swap_b32_e32 v87, v83
	v_permlane16_swap_b32_e32 v88, v84
	v_permlane16_swap_b32_e32 v89, v85
	v_sub_u32_e32 v250, v138, v252
	v_mov_b32_e32 v251, v139
	v_permlane32_swap_b32_e32 v86, v82
	v_permlane32_swap_b32_e32 v87, v83
	v_permlane32_swap_b32_e32 v88, v84
	v_permlane32_swap_b32_e32 v89, v85
	s_nop 1
	global_store_dwordx4 v[250:251], v[86:89], off nt
	global_store_dwordx4 v[250:251], v[82:85], off offset:64 nt

.LBB0_200:
	v_add_u32_e32 v142, 48, v154
	s_nop 0
	v_add_u32_e32 v130, s2, v142
	v_ashrrev_i32_e32 v131, 31, v130
	v_lshlrev_b64 v[138:139], 9, v[130:131]
	s_mov_b64 s[86:87], -1
	s_and_b64 vcc, exec, s[8:9]
	v_lshl_add_u64 v[140:141], v[138:139], 1, s[64:65]
	v_lshl_add_u64 v[138:139], v[138:139], 2, s[72:73]
	v_cvt_pk_bf16_f32 v130, v78, v79
	v_cvt_pk_bf16_f32 v131, v80, v81
	v_cvt_pk_bf16_f32 v132, v74, v75
	v_cvt_pk_bf16_f32 v133, v76, v77
	s_cbranch_vccnz .LBB0_202
	v_lshl_add_u64 v[144:145], v[134:135], 1, v[140:141]
	global_store_dwordx4 v[144:145], v[130:133], off
	v_lshl_add_u64 v[144:145], v[134:135], 2, v[138:139]
	s_mov_b64 s[86:87], 0
	v_mbcnt_lo_u32_b32 v252, -1, 0
	v_mbcnt_hi_u32_b32 v252, -1, v252
	v_lshrrev_b32_e32 v252, 4, v252
	v_lshlrev_b32_e32 v252, 4, v252
	v_permlane16_swap_b32_e32 v78, v74
	v_permlane16_swap_b32_e32 v79, v75
	v_permlane16_swap_b32_e32 v80, v76
	v_permlane16_swap_b32_e32 v81, v77
	v_sub_u32_e32 v250, v144, v252
	v_mov_b32_e32 v251, v145
	v_permlane32_swap_b32_e32 v78, v74
	v_permlane32_swap_b32_e32 v79, v75
	v_permlane32_swap_b32_e32 v80, v76
	v_permlane32_swap_b32_e32 v81, v77
	s_nop 1
	global_store_dwordx4 v[250:251], v[78:81], off nt
	global_store_dwordx4 v[250:251], v[74:77], off offset:64 nt

.LBB0_204:
	s_and_b64 vcc, exec, s[8:9]
	s_mov_b64 s[86:87], -1
	v_cvt_pk_bf16_f32 v130, v70, v71
	v_cvt_pk_bf16_f32 v131, v72, v73
	v_cvt_pk_bf16_f32 v132, v66, v67
	v_cvt_pk_bf16_f32 v133, v68, v69
	s_cbranch_vccnz .LBB0_206
	v_lshl_add_u64 v[140:141], v[136:137], 1, v[140:141]
	v_lshl_add_u64 v[138:139], v[136:137], 2, v[138:139]
	s_mov_b64 s[86:87], 0
	global_store_dwordx4 v[140:141], v[130:133], off
	v_mbcnt_lo_u32_b32 v252, -1, 0
	v_mbcnt_hi_u32_b32 v252, -1, v252
	v_lshrrev_b32_e32 v252, 4, v252
	v_lshlrev_b32_e32 v252, 4, v252
	v_permlane16_swap_b32_e32 v70, v66
	v_permlane16_swap_b32_e32 v71, v67
	v_permlane16_swap_b32_e32 v72, v68
	v_permlane16_swap_b32_e32 v73, v69
	v_sub_u32_e32 v250, v138, v252
	v_mov_b32_e32 v251, v139
	v_permlane32_swap_b32_e32 v70, v66
	v_permlane32_swap_b32_e32 v71, v67
	v_permlane32_swap_b32_e32 v72, v68
	v_permlane32_swap_b32_e32 v73, v69
	s_nop 1
	global_store_dwordx4 v[250:251], v[70:73], off nt
	global_store_dwordx4 v[250:251], v[66:69], off offset:64 nt

.LBB0_208:
	v_add_u32_e32 v142, 0x80, v154
	s_nop 0
	v_add_u32_e32 v130, s2, v142
	v_ashrrev_i32_e32 v131, 31, v130
	v_lshlrev_b64 v[138:139], 9, v[130:131]
	s_mov_b64 s[86:87], -1
	s_and_b64 vcc, exec, s[8:9]
	v_lshl_add_u64 v[140:141], v[138:139], 1, s[64:65]
	v_lshl_add_u64 v[138:139], v[138:139], 2, s[72:73]
	v_cvt_pk_bf16_f32 v130, v62, v63
	v_cvt_pk_bf16_f32 v131, v64, v65
	v_cvt_pk_bf16_f32 v132, v58, v59
	v_cvt_pk_bf16_f32 v133, v60, v61
	s_cbranch_vccnz .LBB0_210
	v_lshl_add_u64 v[144:145], v[134:135], 1, v[140:141]
	global_store_dwordx4 v[144:145], v[130:133], off
	v_lshl_add_u64 v[144:145], v[134:135], 2, v[138:139]
	s_mov_b64 s[86:87], 0
	v_mbcnt_lo_u32_b32 v252, -1, 0
	v_mbcnt_hi_u32_b32 v252, -1, v252
	v_lshrrev_b32_e32 v252, 4, v252
	v_lshlrev_b32_e32 v252, 4, v252
	v_permlane16_swap_b32_e32 v62, v58
	v_permlane16_swap_b32_e32 v63, v59
	v_permlane16_swap_b32_e32 v64, v60
	v_permlane16_swap_b32_e32 v65, v61
	v_sub_u32_e32 v250, v144, v252
	v_mov_b32_e32 v251, v145
	v_permlane32_swap_b32_e32 v62, v58
	v_permlane32_swap_b32_e32 v63, v59
	v_permlane32_swap_b32_e32 v64, v60
	v_permlane32_swap_b32_e32 v65, v61
	s_nop 1
	global_store_dwordx4 v[250:251], v[62:65], off nt
	global_store_dwordx4 v[250:251], v[58:61], off offset:64 nt

.LBB0_212:
	s_and_b64 vcc, exec, s[8:9]
	s_mov_b64 s[86:87], -1
	v_cvt_pk_bf16_f32 v130, v54, v55
	v_cvt_pk_bf16_f32 v131, v56, v57
	v_cvt_pk_bf16_f32 v132, v50, v51
	v_cvt_pk_bf16_f32 v133, v52, v53
	s_cbranch_vccnz .LBB0_214
	v_lshl_add_u64 v[140:141], v[136:137], 1, v[140:141]
	v_lshl_add_u64 v[138:139], v[136:137], 2, v[138:139]
	s_mov_b64 s[86:87], 0
	global_store_dwordx4 v[140:141], v[130:133], off
	v_mbcnt_lo_u32_b32 v252, -1, 0
	v_mbcnt_hi_u32_b32 v252, -1, v252
	v_lshrrev_b32_e32 v252, 4, v252
	v_lshlrev_b32_e32 v252, 4, v252
	v_permlane16_swap_b32_e32 v54, v50
	v_permlane16_swap_b32_e32 v55, v51
	v_permlane16_swap_b32_e32 v56, v52
	v_permlane16_swap_b32_e32 v57, v53
	v_sub_u32_e32 v250, v138, v252
	v_mov_b32_e32 v251, v139
	v_permlane32_swap_b32_e32 v54, v50
	v_permlane32_swap_b32_e32 v55, v51
	v_permlane32_swap_b32_e32 v56, v52
	v_permlane32_swap_b32_e32 v57, v53
	s_nop 1
	global_store_dwordx4 v[250:251], v[54:57], off nt
	global_store_dwordx4 v[250:251], v[50:53], off offset:64 nt

.LBB0_216:
	v_add_u32_e32 v142, 0x90, v154
	s_nop 0
	v_add_u32_e32 v130, s2, v142
	v_ashrrev_i32_e32 v131, 31, v130
	v_lshlrev_b64 v[138:139], 9, v[130:131]
	s_mov_b64 s[86:87], -1
	s_and_b64 vcc, exec, s[8:9]
	v_lshl_add_u64 v[140:141], v[138:139], 1, s[64:65]
	v_lshl_add_u64 v[138:139], v[138:139], 2, s[72:73]
	v_cvt_pk_bf16_f32 v130, v46, v47
	v_cvt_pk_bf16_f32 v131, v48, v49
	v_cvt_pk_bf16_f32 v132, v42, v43
	v_cvt_pk_bf16_f32 v133, v44, v45
	s_cbranch_vccnz .LBB0_218
	v_lshl_add_u64 v[144:145], v[134:135], 1, v[140:141]
	global_store_dwordx4 v[144:145], v[130:133], off
	v_lshl_add_u64 v[144:145], v[134:135], 2, v[138:139]
	s_mov_b64 s[86:87], 0
	v_mbcnt_lo_u32_b32 v252, -1, 0
	v_mbcnt_hi_u32_b32 v252, -1, v252
	v_lshrrev_b32_e32 v252, 4, v252
	v_lshlrev_b32_e32 v252, 4, v252
	v_permlane16_swap_b32_e32 v46, v42
	v_permlane16_swap_b32_e32 v47, v43
	v_permlane16_swap_b32_e32 v48, v44
	v_permlane16_swap_b32_e32 v49, v45
	v_sub_u32_e32 v250, v144, v252
	v_mov_b32_e32 v251, v145
	v_permlane32_swap_b32_e32 v46, v42
	v_permlane32_swap_b32_e32 v47, v43
	v_permlane32_swap_b32_e32 v48, v44
	v_permlane32_swap_b32_e32 v49, v45
	s_nop 1
	global_store_dwordx4 v[250:251], v[46:49], off nt
	global_store_dwordx4 v[250:251], v[42:45], off offset:64 nt

.LBB0_220:
	s_and_b64 vcc, exec, s[8:9]
	s_mov_b64 s[86:87], -1
	v_cvt_pk_bf16_f32 v130, v38, v39
	v_cvt_pk_bf16_f32 v131, v40, v41
	v_cvt_pk_bf16_f32 v132, v34, v35
	v_cvt_pk_bf16_f32 v133, v36, v37
	s_cbranch_vccnz .LBB0_222
	v_lshl_add_u64 v[140:141], v[136:137], 1, v[140:141]
	v_lshl_add_u64 v[138:139], v[136:137], 2, v[138:139]
	s_mov_b64 s[86:87], 0
	global_store_dwordx4 v[140:141], v[130:133], off
	v_mbcnt_lo_u32_b32 v252, -1, 0
	v_mbcnt_hi_u32_b32 v252, -1, v252
	v_lshrrev_b32_e32 v252, 4, v252
	v_lshlrev_b32_e32 v252, 4, v252
	v_permlane16_swap_b32_e32 v38, v34
	v_permlane16_swap_b32_e32 v39, v35
	v_permlane16_swap_b32_e32 v40, v36
	v_permlane16_swap_b32_e32 v41, v37
	v_sub_u32_e32 v250, v138, v252
	v_mov_b32_e32 v251, v139
	v_permlane32_swap_b32_e32 v38, v34
	v_permlane32_swap_b32_e32 v39, v35
	v_permlane32_swap_b32_e32 v40, v36
	v_permlane32_swap_b32_e32 v41, v37
	s_nop 1
	global_store_dwordx4 v[250:251], v[38:41], off nt
	global_store_dwordx4 v[250:251], v[34:37], off offset:64 nt

.LBB0_224:
	v_add_u32_e32 v142, 0xa0, v154
	s_nop 0
	v_add_u32_e32 v130, s2, v142
	v_ashrrev_i32_e32 v131, 31, v130
	v_lshlrev_b64 v[138:139], 9, v[130:131]
	s_mov_b64 s[86:87], -1
	s_and_b64 vcc, exec, s[8:9]
	v_lshl_add_u64 v[140:141], v[138:139], 1, s[64:65]
	v_lshl_add_u64 v[138:139], v[138:139], 2, s[72:73]
	v_cvt_pk_bf16_f32 v130, v30, v31
	v_cvt_pk_bf16_f32 v131, v32, v33
	v_cvt_pk_bf16_f32 v132, v26, v27
	v_cvt_pk_bf16_f32 v133, v28, v29
	s_cbranch_vccnz .LBB0_226
	v_lshl_add_u64 v[144:145], v[134:135], 1, v[140:141]
	global_store_dwordx4 v[144:145], v[130:133], off
	v_lshl_add_u64 v[144:145], v[134:135], 2, v[138:139]
	s_mov_b64 s[86:87], 0
	v_mbcnt_lo_u32_b32 v252, -1, 0
	v_mbcnt_hi_u32_b32 v252, -1, v252
	v_lshrrev_b32_e32 v252, 4, v252
	v_lshlrev_b32_e32 v252, 4, v252
	v_permlane16_swap_b32_e32 v30, v26
	v_permlane16_swap_b32_e32 v31, v27
	v_permlane16_swap_b32_e32 v32, v28
	v_permlane16_swap_b32_e32 v33, v29
	v_sub_u32_e32 v250, v144, v252
	v_mov_b32_e32 v251, v145
	v_permlane32_swap_b32_e32 v30, v26
	v_permlane32_swap_b32_e32 v31, v27
	v_permlane32_swap_b32_e32 v32, v28
	v_permlane32_swap_b32_e32 v33, v29
	s_nop 1
	global_store_dwordx4 v[250:251], v[30:33], off nt
	global_store_dwordx4 v[250:251], v[26:29], off offset:64 nt

.LBB0_228:
	s_and_b64 vcc, exec, s[8:9]
	s_mov_b64 s[86:87], -1
	v_cvt_pk_bf16_f32 v130, v22, v23
	v_cvt_pk_bf16_f32 v131, v24, v25
	v_cvt_pk_bf16_f32 v132, v18, v19
	v_cvt_pk_bf16_f32 v133, v20, v21
	s_cbranch_vccnz .LBB0_230
	v_lshl_add_u64 v[140:141], v[136:137], 1, v[140:141]
	v_lshl_add_u64 v[138:139], v[136:137], 2, v[138:139]
	s_mov_b64 s[86:87], 0
	global_store_dwordx4 v[140:141], v[130:133], off
	v_mbcnt_lo_u32_b32 v252, -1, 0
	v_mbcnt_hi_u32_b32 v252, -1, v252
	v_lshrrev_b32_e32 v252, 4, v252
	v_lshlrev_b32_e32 v252, 4, v252
	v_permlane16_swap_b32_e32 v22, v18
	v_permlane16_swap_b32_e32 v23, v19
	v_permlane16_swap_b32_e32 v24, v20
	v_permlane16_swap_b32_e32 v25, v21
	v_sub_u32_e32 v250, v138, v252
	v_mov_b32_e32 v251, v139
	v_permlane32_swap_b32_e32 v22, v18
	v_permlane32_swap_b32_e32 v23, v19
	v_permlane32_swap_b32_e32 v24, v20
	v_permlane32_swap_b32_e32 v25, v21
	s_nop 1
	global_store_dwordx4 v[250:251], v[22:25], off nt
	global_store_dwordx4 v[250:251], v[18:21], off offset:64 nt

.LBB0_232:
	v_add_u32_e32 v142, 0xb0, v154
	s_nop 0
	v_add_u32_e32 v130, s2, v142
	v_ashrrev_i32_e32 v131, 31, v130
	v_lshlrev_b64 v[138:139], 9, v[130:131]
	s_mov_b64 s[86:87], -1
	s_and_b64 vcc, exec, s[8:9]
	v_lshl_add_u64 v[140:141], v[138:139], 1, s[64:65]
	v_lshl_add_u64 v[138:139], v[138:139], 2, s[72:73]
	v_cvt_pk_bf16_f32 v130, v14, v15
	v_cvt_pk_bf16_f32 v131, v16, v17
	v_cvt_pk_bf16_f32 v132, v10, v11
	v_cvt_pk_bf16_f32 v133, v12, v13
	s_cbranch_vccnz .LBB0_234
	v_lshl_add_u64 v[144:145], v[134:135], 1, v[140:141]
	global_store_dwordx4 v[144:145], v[130:133], off
	v_lshl_add_u64 v[144:145], v[134:135], 2, v[138:139]
	s_mov_b64 s[86:87], 0
	v_mbcnt_lo_u32_b32 v252, -1, 0
	v_mbcnt_hi_u32_b32 v252, -1, v252
	v_lshrrev_b32_e32 v252, 4, v252
	v_lshlrev_b32_e32 v252, 4, v252
	v_permlane16_swap_b32_e32 v14, v10
	v_permlane16_swap_b32_e32 v15, v11
	v_permlane16_swap_b32_e32 v16, v12
	v_permlane16_swap_b32_e32 v17, v13
	v_sub_u32_e32 v250, v144, v252
	v_mov_b32_e32 v251, v145
	v_permlane32_swap_b32_e32 v14, v10
	v_permlane32_swap_b32_e32 v15, v11
	v_permlane32_swap_b32_e32 v16, v12
	v_permlane32_swap_b32_e32 v17, v13
	s_nop 1
	global_store_dwordx4 v[250:251], v[14:17], off nt
	global_store_dwordx4 v[250:251], v[10:13], off offset:64 nt

.LBB0_236:
	s_and_b64 vcc, exec, s[8:9]
	s_mov_b64 s[8:9], -1
	v_cvt_pk_bf16_f32 v130, v6, v7
	v_cvt_pk_bf16_f32 v131, v8, v9
	v_cvt_pk_bf16_f32 v132, v2, v3
	v_cvt_pk_bf16_f32 v133, v4, v5
	s_cbranch_vccnz .LBB0_238
	v_lshl_add_u64 v[134:135], v[136:137], 1, v[140:141]
	global_store_dwordx4 v[134:135], v[130:133], off
	v_lshl_add_u64 v[134:135], v[136:137], 2, v[138:139]
	s_mov_b64 s[8:9], 0
	v_mbcnt_lo_u32_b32 v252, -1, 0
	v_mbcnt_hi_u32_b32 v252, -1, v252
	v_lshrrev_b32_e32 v252, 4, v252
	v_lshlrev_b32_e32 v252, 4, v252
	v_permlane16_swap_b32_e32 v6, v2
	v_permlane16_swap_b32_e32 v7, v3
	v_permlane16_swap_b32_e32 v8, v4
	v_permlane16_swap_b32_e32 v9, v5
	v_sub_u32_e32 v250, v134, v252
	v_mov_b32_e32 v251, v135
	v_permlane32_swap_b32_e32 v6, v2
	v_permlane32_swap_b32_e32 v7, v3
	v_permlane32_swap_b32_e32 v8, v4
	v_permlane32_swap_b32_e32 v9, v5
	s_nop 1
	global_store_dwordx4 v[250:251], v[6:9], off nt
	global_store_dwordx4 v[250:251], v[2:5], off offset:64 nt

.LBB0_431:
	v_readlane_b32 s2, v255, 5
	s_cmpk_lt_u32 s92, 0x80
	v_readlane_b32 s3, v255, 6
	s_cselect_b64 s[0:1], -1, 0
	s_xor_b64 s[2:3], s[2:3], -1
	s_or_b64 s[0:1], s[0:1], s[2:3]
	s_and_b64 vcc, exec, s[0:1]
	s_cbranch_vccnz .LBB0_465
	s_load_dwordx2 s[98:99], s[90:91], 0x18
	s_load_dwordx2 s[100:101], s[90:91], 0x20
	v_lshl_or_b32 v200, s92, 9, v0
	v_add_u32_e32 v200, 0xffff0000, v200
	v_lshlrev_b32_e32 v201, 3, v200
	v_add_u32_e32 v202, 0x80000, v201
	v_and_b32_e32 v203, 0xffffffc0, v201
	v_lshrrev_b32_e32 v209, 1, v201
	v_and_or_b32 v203, v209, 28, v203
	v_or_b32_e32 v204, 32, v203
	v_lshlrev_b32_e32 v203, 2, v203
	v_lshlrev_b32_e32 v204, 2, v204
	v_and_b32_e32 v205, 0xffffffc0, v202
	v_lshrrev_b32_e32 v210, 1, v202
	v_and_or_b32 v205, v210, 28, v205
	v_or_b32_e32 v206, 32, v205
	v_lshlrev_b32_e32 v205, 2, v205
	v_lshlrev_b32_e32 v206, 2, v206
	v_lshlrev_b32_e32 v207, 2, v201
	v_lshlrev_b32_e32 v208, 2, v202
	s_waitcnt lgkmcnt(0)
	global_load_dwordx4 v[212:215], v203, s[98:99] nt
	global_load_dwordx4 v[216:219], v204, s[98:99] nt
	global_load_dwordx4 v[220:223], v205, s[98:99] nt
	global_load_dwordx4 v[224:227], v206, s[98:99] nt
	global_load_dwordx4 v[228:231], v207, s[100:101] nt
	global_load_dwordx4 v[232:235], v207, s[100:101] offset:16 nt
	global_load_dwordx4 v[236:239], v208, s[100:101] nt
	global_load_dwordx4 v[240:243], v208, s[100:101] offset:16 nt
	v_lshrrev_b32_e32 v244, 18, v201
	v_mul_u32_u24_e32 v244, 0x180000, v244
	v_and_b32_e32 v209, 0x3ffff, v201
	v_lshl_add_u32 v244, v209, 1, v244
	v_lshrrev_b32_e32 v245, 18, v202
	v_mul_u32_u24_e32 v245, 0x180000, v245
	v_and_b32_e32 v209, 0x3ffff, v202
	v_lshl_add_u32 v245, v209, 1, v245
	v_add_u32_e32 v246, 0x8800000, v244
	v_add_u32_e32 v247, 0x8800000, v245
	v_add_u32_e32 v248, 0x8e00000, v244
	v_add_u32_e32 v249, 0x8e00000, v245
	v_mov_b32_e32 v4, v0
	v_mov_b32_e32 v51, v1
	s_cmpk_gt_i32 s92, 0xff
	v_ashrrev_i32_e32 v50, 4, v51
	s_cbranch_scc1 .LBB0_441
	s_mov_b64 s[0:1], s[90:91]
	s_load_dwordx2 s[0:1], s[0:1], 0x10
	s_mov_b64 s[2:3], s[90:91]
	s_load_dwordx2 s[2:3], s[2:3], 0x30
	v_lshlrev_b32_e32 v2, 2, v4
	v_ashrrev_i32_e32 v3, 31, v2
	s_mov_b64 s[4:5], s[90:91]
	v_lshlrev_b64 v[2:3], 2, v[2:3]
	s_mov_b64 s[8:9], s[90:91]
	s_waitcnt lgkmcnt(0)
	v_lshl_add_u64 v[22:23], s[0:1], 0, v[2:3]
	s_load_dwordx2 s[4:5], s[4:5], 0x38
	global_load_dwordx4 v[6:9], v[22:23], off
	v_lshl_add_u64 v[2:3], s[2:3], 0, v[2:3]
	s_movk_i32 s0, 0x2000
	global_load_dwordx4 v[10:13], v[2:3], off
	v_add_co_u32_e32 v2, vcc, s0, v22
	s_movk_i32 s0, 0x4000
	s_nop 0
	v_addc_co_u32_e32 v3, vcc, 0, v23, vcc
	global_load_dwordx4 v[14:17], v[2:3], off
	v_add_co_u32_e32 v2, vcc, s0, v22
	s_movk_i32 s0, 0x6000
	s_nop 0
	v_addc_co_u32_e32 v3, vcc, 0, v23, vcc
	global_load_dwordx4 v[18:21], v[2:3], off
	v_add_co_u32_e32 v2, vcc, s0, v22
	v_lshl_add_u32 v5, v4, 4, 0
	s_nop 0
	v_addc_co_u32_e32 v3, vcc, 0, v23, vcc
	global_load_dwordx4 v[22:25], v[2:3], off
	s_load_dwordx2 s[8:9], s[8:9], 0x40
	s_lshl_b32 s1, s83, 10
	s_add_i32 s1, s1, 0
	v_lshl_add_u32 v53, v50, 2, s1
	s_movk_i32 s1, 0xf0
	s_mov_b32 s7, 0
	s_mul_i32 s10, s83, 0x3c0
	s_mov_b32 s12, 0x60000
	s_mov_b32 s13, 0x78000
	s_mov_b32 s14, 0x90000
	s_mov_b32 s15, 0xa8000
	v_mov_b32_e32 v56, 0x3000000
	s_mov_b32 s16, s92
	s_waitcnt vmcnt(0)
	v_mul_f32_e32 v2, 0xbfb8aa3b, v6
	v_mul_f32_e32 v3, 0xbfb8aa3b, v7
	v_exp_f32_e32 v2, v2
	v_exp_f32_e32 v3, v3
	v_mul_f32_e32 v26, 0xbfb8aa3b, v8
	v_mul_f32_e32 v27, 0xbfb8aa3b, v9
	v_mul_f32_e32 v28, 0xbfb8aa3b, v10
	v_mul_f32_e32 v29, 0xbfb8aa3b, v11
	v_mul_f32_e32 v30, 0xbfb8aa3b, v12
	v_mul_f32_e32 v31, 0xbfb8aa3b, v13
	v_exp_f32_e32 v26, v26
	v_exp_f32_e32 v27, v27
	v_mul_f32_e32 v32, 0xbfb8aa3b, v14
	v_mul_f32_e32 v33, 0xbfb8aa3b, v15
	v_mul_f32_e32 v34, 0xbfb8aa3b, v16
	v_mul_f32_e32 v35, 0xbfb8aa3b, v17
	v_exp_f32_e32 v28, v28
	v_exp_f32_e32 v29, v29
	v_exp_f32_e32 v30, v30
	v_exp_f32_e32 v31, v31
	v_exp_f32_e32 v32, v32
	v_exp_f32_e32 v33, v33
	v_add_f32_e32 v2, 1.0, v2
	v_add_f32_e32 v3, 1.0, v3
	v_exp_f32_e32 v34, v34
	v_exp_f32_e32 v35, v35
	v_rcp_f32_e32 v2, v2
	v_rcp_f32_e32 v3, v3
	v_add_f32_e32 v26, 1.0, v26
	v_add_f32_e32 v27, 1.0, v27
	v_add_f32_e32 v28, 1.0, v28
	v_add_f32_e32 v29, 1.0, v29
	v_add_f32_e32 v30, 1.0, v30
	v_add_f32_e32 v31, 1.0, v31
	v_rcp_f32_e32 v26, v26
	v_rcp_f32_e32 v27, v27
	v_add_f32_e32 v32, 1.0, v32
	v_add_f32_e32 v33, 1.0, v33
	v_add_f32_e32 v34, 1.0, v34
	v_add_f32_e32 v35, 1.0, v35
	v_rcp_f32_e32 v28, v28
	v_rcp_f32_e32 v29, v29
	v_rcp_f32_e32 v30, v30
	v_rcp_f32_e32 v31, v31
	v_rcp_f32_e32 v32, v32
	v_rcp_f32_e32 v33, v33
	v_pk_mul_f32 v[6:7], v[6:7], v[2:3]
	v_mul_f32_e32 v2, 0xbfb8aa3b, v20
	v_mul_f32_e32 v3, 0xbfb8aa3b, v21
	v_rcp_f32_e32 v34, v34
	v_rcp_f32_e32 v35, v35
	v_exp_f32_e32 v2, v2
	v_exp_f32_e32 v3, v3
	v_pk_mul_f32 v[8:9], v[8:9], v[26:27]
	v_mul_f32_e32 v37, 0xbfb8aa3b, v19
	v_pk_mul_f32 v[12:13], v[12:13], v[30:31]
	v_pk_mul_f32 v[10:11], v[10:11], v[28:29]
	ds_write_b128 v5, v[6:9] offset:8192
	v_pk_mul_f32 v[6:7], v[14:15], v[32:33]
	v_pk_mul_f32 v[8:9], v[16:17], v[34:35]
	ds_write_b128 v5, v[10:13]
	ds_write_b128 v5, v[6:9] offset:16384
	v_exp_f32_e32 v6, v37
	v_add_f32_e32 v2, 1.0, v2
	v_add_f32_e32 v3, 1.0, v3
	v_rcp_f32_e32 v2, v2
	v_rcp_f32_e32 v3, v3
	v_mul_f32_e32 v7, 0xbfb8aa3b, v22
	v_exp_f32_e32 v7, v7
	v_mul_f32_e32 v36, 0xbfb8aa3b, v18
	v_add_f32_e32 v6, 1.0, v6
	v_exp_f32_e32 v36, v36
	v_rcp_f32_e32 v37, v6
	v_pk_mul_f32 v[8:9], v[20:21], v[2:3]
	v_mul_f32_e32 v3, 0xbfb8aa3b, v23
	v_mul_f32_e32 v6, 0xbfb8aa3b, v24
	v_add_f32_e32 v2, 1.0, v7
	v_exp_f32_e32 v3, v3
	v_exp_f32_e32 v6, v6
	v_mul_f32_e32 v7, 0xbfb8aa3b, v25
	v_exp_f32_e32 v7, v7
	v_add_f32_e32 v36, 1.0, v36
	v_rcp_f32_e32 v36, v36
	v_add_f32_e32 v3, 1.0, v3
	v_add_f32_e32 v6, 1.0, v6
	v_rcp_f32_e32 v2, v2
	v_rcp_f32_e32 v10, v6
	v_add_f32_e32 v6, 1.0, v7
	v_rcp_f32_e32 v3, v3
	v_rcp_f32_e32 v11, v6
	v_pk_mul_f32 v[6:7], v[18:19], v[36:37]
	ds_write_b128 v5, v[6:9] offset:24576
	v_pk_mul_f32 v[6:7], v[22:23], v[2:3]
	v_mbcnt_lo_u32_b32 v2, -1, 0
	v_pk_mul_f32 v[8:9], v[24:25], v[10:11]
	v_mbcnt_hi_u32_b32 v2, -1, v2
	ds_write_b128 v5, v[6:9] offset:32768
	v_and_b32_e32 v5, 64, v2
	v_xor_b32_e32 v3, 16, v2
	v_add_u32_e32 v5, 64, v5
	v_cmp_lt_i32_e32 vcc, v3, v5
	v_xor_b32_e32 v6, 32, v2
	v_lshl_add_u32 v10, v51, 4, 0
	v_cndmask_b32_e32 v3, v2, v3, vcc
	v_cmp_lt_i32_e32 vcc, v6, v5
	v_lshl_add_u32 v5, s83, 8, v50
	v_lshlrev_b32_e32 v3, 2, v3
	v_cndmask_b32_e32 v2, v2, v6, vcc
	v_lshlrev_b32_e32 v52, 2, v2
	v_and_b32_e32 v2, 15, v51
	s_waitcnt lgkmcnt(0)
	v_mov_b64_e32 v[6:7], s[4:5]
	v_cmp_gt_i32_e64 s[4:5], s1, v4
	s_mov_b32 s1, 0x2aaaaaab
	v_mad_i64_i32 v[6:7], s[2:3], v5, s0, v[6:7]
	v_lshlrev_b32_e32 v5, 2, v2
	v_cmp_gt_u32_e32 vcc, 12, v2
	v_mul_hi_i32 v2, v4, s1
	v_lshrrev_b32_e32 v8, 31, v2
	v_ashrrev_i32_e32 v2, 3, v2
	v_add_u32_e32 v2, v2, v8
	s_movk_i32 s1, 0xc0
	v_mul_lo_u32 v12, v2, s1
	s_and_b32 s1, s92, 0x7f
	s_mul_i32 s1, s1, 48
	v_mul_lo_u32 v8, v2, 48
	s_lshl_b32 s6, s1, 2
	v_cndmask_b32_e32 v5, 0, v5, vcc
	v_sub_u32_e32 v8, v4, v8
	s_add_u32 s2, s86, s6
	v_lshl_add_u32 v11, v8, 2, 0
	v_ashrrev_i32_e32 v9, 31, v8
	v_lshl_add_u64 v[6:7], v[6:7], 0, s[6:7]
	v_lshlrev_b32_e32 v4, 2, v5
	v_mov_b32_e32 v5, 0
	s_addc_u32 s3, s87, 0
	v_cmp_gt_i32_e32 vcc, 12, v51
	v_lshl_add_u64 v[6:7], v[6:7], 0, v[4:5]
	v_add_u32_e32 v4, s1, v8
	v_lshl_add_u64 v[8:9], v[8:9], 2, s[2:3]
	s_mov_b32 s1, 0x18000
	s_mov_b32 s2, 0x30000
	s_mov_b32 s3, 0x48000
	v_add_u32_e32 v54, s10, v10
	v_add_u32_e32 v55, v11, v12
	s_barrier
	s_branch .LBB0_435

.LBB0_464:
	v_cvt_pk_bf16_f32 v212, v212, v213
	v_cvt_pk_bf16_f32 v213, v214, v215
	v_cvt_pk_bf16_f32 v214, v216, v217
	v_cvt_pk_bf16_f32 v215, v218, v219
	global_store_dwordx4 v246, v[212:215], s[18:19]
	v_cvt_pk_bf16_f32 v220, v220, v221
	v_cvt_pk_bf16_f32 v221, v222, v223
	v_cvt_pk_bf16_f32 v222, v224, v225
	v_cvt_pk_bf16_f32 v223, v226, v227
	global_store_dwordx4 v247, v[220:223], s[18:19]
	v_cvt_pk_bf16_f32 v228, v228, v229
	v_cvt_pk_bf16_f32 v229, v230, v231
	v_cvt_pk_bf16_f32 v230, v232, v233
	v_cvt_pk_bf16_f32 v231, v234, v235
	global_store_dwordx4 v248, v[228:231], s[18:19]
	v_cvt_pk_bf16_f32 v236, v236, v237
	v_cvt_pk_bf16_f32 v237, v238, v239
	v_cvt_pk_bf16_f32 v238, v240, v241
	v_cvt_pk_bf16_f32 v239, v242, v243
	global_store_dwordx4 v249, v[236:239], s[18:19]
	v_readlane_b32 s23, v255, 7
